# mamba partial-sum reduction as one straight-line pass (8 LDS reads in flight)
# baseline (speedup 1.0000x reference)
.LBB0_673:
	v_ashrrev_i32_e32 v1, 4, v0
	v_lshl_add_u32 v16, v1, 10, v86
	ds_read_b128 v[8:11], v16 offset:37376
	ds_read_b128 v[12:15], v16 offset:37392
	ds_read_b128 v[38:41], v16 offset:37408
	ds_read_b128 v[42:45], v16 offset:37424
	v_add_u32_e32 v146, 0x100, v0
	v_ashrrev_i32_e32 v147, 4, v146
	v_lshl_add_u32 v148, v147, 10, v86
	ds_read_b128 v[130:133], v148 offset:37376
	ds_read_b128 v[134:137], v148 offset:37392
	ds_read_b128 v[138:141], v148 offset:37408
	ds_read_b128 v[142:145], v148 offset:37424
	s_waitcnt lgkmcnt(7)
	v_mov_b32_e32 v46, v9
	v_mov_b32_e32 v47, v10
	v_mov_b32_e32 v9, v11
	s_waitcnt lgkmcnt(6)
	v_mov_b32_e32 v10, v13
	v_mov_b32_e32 v11, v14
	v_mov_b32_e32 v13, v15
	v_pk_add_f32 v[8:9], v[46:47], v[8:9]
	v_pk_add_f32 v[10:11], v[10:11], v[12:13]
	v_pk_add_f32 v[8:9], v[8:9], v[8:9] op_sel:[0,1] op_sel_hi:[1,0]
	v_pk_add_f32 v[10:11], v[10:11], v[10:11] op_sel:[0,1] op_sel_hi:[1,0]
	s_waitcnt lgkmcnt(5)
	v_add_f32_e32 v12, v38, v39
	v_add_f32_e32 v14, v40, v41
	s_waitcnt lgkmcnt(4)
	v_mov_b32_e32 v9, v42
	v_mov_b32_e32 v11, v43
	v_mov_b32_e32 v13, v44
	v_mov_b32_e32 v15, v45
	v_pk_add_f32 v[8:9], v[8:9], v[10:11]
	v_pk_add_f32 v[10:11], v[12:13], v[14:15]
	v_pk_add_f32 v[8:9], v[8:9], v[10:11]
	v_add_f32_e32 v8, v8, v9
	v_cvt_pk_bf16_f32 v10, v8, v17
	v_add_u32_e32 v8, s25, v1
	v_ashrrev_i32_e32 v9, 31, v8
	v_lshlrev_b64 v[8:9], 11, v[8:9]
	v_lshl_add_u64 v[8:9], v[50:51], 0, v[8:9]
	global_store_short v[8:9], v10, off
	s_waitcnt lgkmcnt(3)
	v_mov_b32_e32 v150, v131
	v_mov_b32_e32 v151, v132
	v_mov_b32_e32 v131, v133
	s_waitcnt lgkmcnt(2)
	v_mov_b32_e32 v132, v135
	v_mov_b32_e32 v133, v136
	v_mov_b32_e32 v135, v137
	v_pk_add_f32 v[130:131], v[150:151], v[130:131]
	v_pk_add_f32 v[132:133], v[132:133], v[134:135]
	v_pk_add_f32 v[130:131], v[130:131], v[130:131] op_sel:[0,1] op_sel_hi:[1,0]
	v_pk_add_f32 v[132:133], v[132:133], v[132:133] op_sel:[0,1] op_sel_hi:[1,0]
	s_waitcnt lgkmcnt(1)
	v_add_f32_e32 v134, v138, v139
	v_add_f32_e32 v136, v140, v141
	s_waitcnt lgkmcnt(0)
	v_mov_b32_e32 v131, v142
	v_mov_b32_e32 v133, v143
	v_mov_b32_e32 v135, v144
	v_mov_b32_e32 v137, v145
	v_pk_add_f32 v[130:131], v[130:131], v[132:133]
	v_pk_add_f32 v[132:133], v[134:135], v[136:137]
	v_pk_add_f32 v[130:131], v[130:131], v[132:133]
	v_add_f32_e32 v130, v130, v131
	v_cvt_pk_bf16_f32 v132, v130, v17
	v_add_u32_e32 v130, s25, v147
	v_ashrrev_i32_e32 v131, 31, v130
	v_lshlrev_b64 v[130:131], 11, v[130:131]
	v_lshl_add_u64 v[130:131], v[50:51], 0, v[130:131]
	global_store_short v[130:131], v132, off
